# static priority raise (s_setprio 1) for waves 4-7 during the P6 prompt attention, reset before the phase barrier
# baseline (speedup 1.0000x reference)
; #define PH(k) for (int r_ = 0, n_ = probe_reps(k); r_ < n_; ++r_)
; __global__ void __launch_bounds__(512, 2) mega_fwd(Args a_unused) {
;     ...
;         if (G == 256) {
;             int a0, an;
;             if (bx >= 252) { a0 = 500 + 3 * (bx - 252); an = 3; } else if (bx >= 4) { a0 = 2 * (bx - 4); an = 2; } else { a0 = 496 + bx; an = 1; }
;             PH(11) for (int it = a0; it < a0 + an; ++it) attn_unit(lds, a, it & 7, 63 - (it >> 3), thr);
.LBB0_853:
	v_readfirstlane_b32 s94, v164
	s_cmpk_lt_u32 s94, 0x100
	s_cbranch_scc1 .Lprio_skip
	s_setprio 1

; __device__ __forceinline__ unsigned xb_add(unsigned* p, unsigned v) { return __hip_atomic_fetch_add(p, v, __ATOMIC_RELAXED, __HIP_MEMORY_SCOPE_AGENT); }
; __device__ __forceinline__ void xcd_barrier(const XcdBarrier& b) {
;     asm volatile("s_waitcnt vmcnt(0)" ::: "memory");
;     __syncthreads();
;     if (threadIdx.x == 0) {
;         unsigned* bar = b.bar;
;         __builtin_amdgcn_s_waitcnt(0);
;         unsigned nloc = b.st[0], nx = b.st[1];
;         if (nloc == 0u) { xcd_barrier_complete(bar, b.x, nloc, nx); b.st[0] = nloc; b.st[1] = nx; }
;         const unsigned old = xb_add(&bar[XB_XSUB(b.x)], 1u);
; __global__ void __launch_bounds__(512, 2) mega_fwd(Args a_unused) {
;     ...
;     grid_bar(lds);
.LBB0_1165:
	s_setprio 0
	s_mov_b64 s[10:11], s[92:93]
	s_getreg_b32 s0, hwreg(HW_REG_XCC_ID, 0, 4)
	s_waitcnt vmcnt(0)
	s_barrier
	s_and_saveexec_b64 s[8:9], s[52:53]
	s_cbranch_execz .LBB0_1217
	s_add_i32 s1, 0, 0x20040
	v_mov_b32_e32 v0, s1
	s_load_dwordx2 s[10:11], s[10:11], 0xf8
	s_waitcnt vmcnt(0) expcnt(0) lgkmcnt(0)
	ds_read_b32 v2, v0
	s_add_i32 s1, 0, 0x20044
	v_mov_b32_e32 v0, s1
	ds_read_b32 v0, v0
	s_and_b32 s0, s0, 15
	s_waitcnt lgkmcnt(1)
	v_cmp_ne_u32_e32 vcc, 0, v2
	s_cbranch_vccnz .LBB0_1181
	s_add_u32 s12, s10, 0x80200
	s_addc_u32 s13, s11, 0
	s_add_u32 s14, s10, 0x80400
	s_addc_u32 s15, s11, 0
	s_add_u32 s16, s10, 0x80500
	s_addc_u32 s17, s11, 0
	s_add_u32 s18, s10, 0x80600
	s_addc_u32 s19, s11, 0
	s_add_u32 s20, s10, 0x80700
	s_addc_u32 s21, s11, 0
	s_add_u32 s22, s10, 0x80800
	s_addc_u32 s23, s11, 0
	s_add_u32 s24, s10, 0x80900
	s_addc_u32 s25, s11, 0
	s_add_u32 s26, s10, 0x80a00
	s_addc_u32 s27, s11, 0
	s_add_u32 s28, s10, 0x80b00
	s_addc_u32 s29, s11, 0
	s_add_u32 s30, s10, 0x80c00
	s_addc_u32 s31, s11, 0
	s_add_u32 s34, s10, 0x80d00
	s_addc_u32 s35, s11, 0
	s_add_u32 s36, s10, 0x80e00
	s_addc_u32 s37, s11, 0
	s_add_u32 s38, s10, 0x80f00
	s_addc_u32 s39, s11, 0
	s_add_u32 s40, s10, 0x81000
	s_addc_u32 s41, s11, 0
	s_add_u32 s42, s10, 0x81100
	s_addc_u32 s43, s11, 0
	s_add_u32 s44, s10, 0x81200
	s_addc_u32 s45, s11, 0
	s_mul_i32 s1, s61, s78
	s_add_u32 s46, s10, 0x81300
	s_mul_i32 s1, s1, s60
	s_addc_u32 s47, s11, 0
	s_mov_b32 s3, 1
	v_mov_b32_e32 v16, 0
	s_branch .LBB0_1169
